# ConvGLU epilogue preamble: gate-bias vector loads issued together with the row-statistics loads (one exposed round trip less per tile)
# baseline (speedup 1.0000x reference)
; #define LAS __attribute__((address_space(3)))
;     __device__ __forceinline__ void operator()(const pg8::f32x4 (&acc)[2][2][4][2], const pg8::Unit& u, int wr, int wc, int fr, int fq) const {
;     ...
;         const float* bpg = bias + (size_t)(u.pm >= 256 ? 16 : (u.pm >> 4)) * FUP + u.pn * 256 + lf;
;         const float* rsp = rowss + u.pm * 256 + wr * 64 + fr;
;         float rsv[2][4];
; #pragma unroll
;         for (int ai = 0; ai < 2; ++ai)
; #pragma unroll
;             for (int m = 0; m < 4; ++m) rsv[ai][m] = rsp[ai * 128 + m * 16];
; #pragma unroll
;         for (int ai = 0; ai < 2; ++ai)
; #pragma unroll
;             for (int m = 0; m < 4; ++m) rsv[ai][m] = rsqrtf(rsv[ai][m] * (1.0f / DM) + EPS);
;     ...
;         {
;             const f32x4 bg0 = *(const f32x4*)bpg, bg1 = *(const f32x4*)(bpg + 4);
; #pragma unroll
;             for (int ai = 0; ai < 2; ++ai) {
;                 const int gi = 2 * ai + wr;
;                 if (fr == 0)  { const float r_ = GLU_RS(ai, 0); *(LAS f32x4*)(xg + (gi * 2 + 0) * 128 + lf) = acc[ai][0][0][0] * r_ + bg0; *(LAS f32x4*)(xg + (gi * 2 + 0) * 128 + lf + 4) = acc[ai][0][0][1] * r_ + bg1; }
;                 if (fr == 15) { const float r_ = GLU_RS(ai, 3); *(LAS f32x4*)(xg + (gi * 2 + 1) * 128 + lf) = acc[ai][0][3][0] * r_ + bg0; *(LAS f32x4*)(xg + (gi * 2 + 1) * 128 + lf + 4) = acc[ai][0][3][1] * r_ + bg1; }
.LBB0_341:
	s_lshl_b32 s60, s80, 8
	s_ashr_i32 s61, s60, 31
	v_lshl_add_u64 v[120:121], s[60:61], 2, v[180:181]
	global_load_dword v122, v[120:121], off
	global_load_dword v151, v[120:121], off offset:64
	global_load_dword v152, v[120:121], off offset:128
	global_load_dword v123, v[120:121], off offset:192
	global_load_dword v136, v[120:121], off offset:512
	global_load_dword v153, v[120:121], off offset:576
	global_load_dword v154, v[120:121], off offset:640
	s_nop 0
	global_load_dword v120, v[120:121], off offset:704
	s_lshl_b32 s4, s34, 8
	s_ashr_i32 s5, s4, 31
	s_lshl_b64 s[0:1], s[0:1], 2
	s_add_u32 s6, s15, s0
	s_addc_u32 s7, s19, s1
	s_lshl_b64 s[0:1], s[4:5], 2
	s_add_u32 s4, s6, s0
	s_addc_u32 s5, s7, s1
	v_lshlrev_b32_e32 v148, 2, v176
	s_mov_b64 s[30:31], s[96:97]
	v_cmp_lt_i32_e64 s[0:1], 14, v174
	s_mov_b64 s[6:7], 0
	global_load_dwordx4 v[242:245], v148, s[4:5] offset:16
	global_load_dwordx4 v[246:249], v148, s[4:5]
	s_waitcnt vmcnt(2)
	v_fmamk_f32 v141, v122, 0x3a800000, v218
	v_cmp_gt_f32_e64 s[46:47], s9, v141
	v_fmamk_f32 v140, v123, 0x3a800000, v218
	v_fmamk_f32 v155, v136, 0x3a800000, v218
	v_cmp_gt_f32_e64 s[48:49], s9, v140
	v_cmp_gt_f32_e32 vcc, s9, v155
	v_fmamk_f32 v149, v120, 0x3a800000, v218
	v_cmp_gt_f32_e64 s[44:45], s9, v149
	s_and_saveexec_b64 s[96:97], s[0:1]
	s_xor_b64 s[0:1], exec, s[96:97]
	s_mov_b64 s[6:7], exec
	s_or_saveexec_b64 s[0:1], s[0:1]
	v_mul_f32_e32 v142, 0x4b800000, v141
	v_cndmask_b32_e64 v141, v141, v142, s[46:47]
	v_mul_f32_e32 v142, 0x4b800000, v140
	v_rsq_f32_e32 v141, v141
	v_cndmask_b32_e64 v140, v140, v142, s[48:49]
	v_rsq_f32_e32 v140, v140
	v_mov_b64_e32 v[146:147], v[106:107]
	v_mul_f32_e32 v142, 0x45800000, v141
	v_cndmask_b32_e64 v206, v141, v142, s[46:47]
	v_mul_f32_e32 v141, 0x45800000, v140
	v_cndmask_b32_e64 v200, v140, v141, s[48:49]
	v_mov_b64_e32 v[142:143], v[70:71]
	v_mov_b32_e32 v156, s23
	v_mov_b64_e32 v[144:145], v[104:105]
	v_mov_b32_e32 v150, v200
	v_mov_b64_e32 v[140:141], v[68:69]
	s_mov_b64 s[96:97], s[30:31]
	s_xor_b64 exec, exec, s[0:1]
	s_andn2_b64 s[6:7], s[6:7], exec
	s_and_b64 s[46:47], s[38:39], exec
	v_mov_b64_e32 v[146:147], v[134:135]
	v_mov_b64_e32 v[142:143], v[94:95]
	v_mov_b32_e32 v156, s22
	s_or_b64 s[6:7], s[6:7], s[46:47]
	v_mov_b64_e32 v[144:145], v[132:133]
	v_mov_b32_e32 v150, v206
	v_mov_b64_e32 v[140:141], v[92:93]
	s_or_b64 exec, exec, s[0:1]
	v_mul_f32_e32 v157, 0x4b800000, v155
	v_cndmask_b32_e32 v155, v155, v157, vcc
	v_mul_f32_e32 v157, 0x4b800000, v149
	v_rsq_f32_e32 v155, v155
	v_cndmask_b32_e64 v149, v149, v157, s[44:45]
	v_rsq_f32_e32 v149, v149
	v_mul_f32_e32 v157, 0x45800000, v155
	v_cndmask_b32_e32 v188, v155, v157, vcc
	v_mul_f32_e32 v155, 0x45800000, v149
	v_cndmask_b32_e64 v186, v149, v155, s[44:45]
	s_and_saveexec_b64 s[0:1], s[6:7]
	s_cbranch_execz .LBB0_352
	s_waitcnt vmcnt(0)
	v_pk_fma_f32 v[146:147], v[146:147], v[150:151], v[248:249] op_sel_hi:[1,0,1]
	v_pk_fma_f32 v[144:145], v[144:145], v[150:151], v[246:247] op_sel_hi:[1,0,1]
	v_lshl_add_u32 v149, v156, 2, v175
	v_pk_fma_f32 v[142:143], v[150:151], v[142:143], v[244:245] op_sel_hi:[0,1,1]
	v_pk_fma_f32 v[140:141], v[150:151], v[140:141], v[242:243] op_sel_hi:[0,1,1]
	ds_write_b128 v149, v[144:147]
	ds_write_b128 v149, v[140:143] offset:16
	v_mov_b64_e32 v[142:143], v[6:7]
	v_mov_b64_e32 v[146:147], v[42:43]
	v_cmp_gt_i32_e32 vcc, 15, v174
	s_mov_b64 s[44:45], -1
	v_mov_b32_e32 v149, s24
	v_mov_b64_e32 v[140:141], v[4:5]
	v_mov_b64_e32 v[144:145], v[40:41]
	v_mov_b32_e32 v150, v186
	s_and_saveexec_b64 s[6:7], vcc
	s_cbranch_execz .LBB0_350
	v_cmp_eq_u32_e32 vcc, 0, v174
	s_mov_b64 s[44:45], 0
	s_and_saveexec_b64 s[46:47], vcc
	s_mov_b64 s[44:45], exec
	s_or_b64 exec, exec, s[46:47]
	v_readlane_b32 s30, v255, 45
	v_mov_b64_e32 v[142:143], v[30:31]
	v_mov_b64_e32 v[146:147], v[66:67]
	v_mov_b32_e32 v149, s30
	s_orn2_b64 s[44:45], s[44:45], exec
	v_mov_b64_e32 v[140:141], v[28:29]
	v_mov_b64_e32 v[144:145], v[64:65]
	v_mov_b32_e32 v150, v188
; #define LAS __attribute__((address_space(3)))
;     __device__ __forceinline__ void operator()(const pg8::f32x4 (&acc)[2][2][4][2], const pg8::Unit& u, int wr, int wc, int fr, int fq) const {
;     ...
;                 if (fr == 0)  { const float r_ = GLU_RS(ai, 0); *(LAS f32x4*)(xg + (gi * 2 + 0) * 128 + lf) = acc[ai][0][0][0] * r_ + bg0; *(LAS f32x4*)(xg + (gi * 2 + 0) * 128 + lf + 4) = acc[ai][0][0][1] * r_ + bg1; }
;                 if (fr == 15) { const float r_ = GLU_RS(ai, 3); *(LAS f32x4*)(xg + (gi * 2 + 1) * 128 + lf) = acc[ai][0][3][0] * r_ + bg0; *(LAS f32x4*)(xg + (gi * 2 + 1) * 128 + lf + 4) = acc[ai][0][3][1] * r_ + bg1; }
;             }
;             if (wr == 0 && fr < 2) {
;                 const float r_ = GLU_RS(0, 0);
;                 float* e = edge + ((size_t)u.pm * 6 + fr) * DFF + f0; *(f32x4*)e = acc[0][0][0][0] * r_ + bg0; *(f32x4*)(e + 4) = acc[0][0][0][1] * r_ + bg1;
;                 if (fr == 0) { const f32x4 bv0 = *(const f32x4*)(bpg + 128), bv1 = *(const f32x4*)(bpg + 132); float* ev = edge + ((size_t)u.pm * 6 + 4) * DFF + f0; *(f32x4*)ev = acc[0][1][0][0] * r_ + bv0; *(f32x4*)(ev + 4) = acc[0][1][0][1] * r_ + bv1; }
;             }
;             if (wr == 1 && fr >= 14) {
;                 const float r_ = GLU_RS(1, 3);
;                 float* e = edge + ((size_t)u.pm * 6 + 2 + (fr - 14)) * DFF + f0; *(f32x4*)e = acc[1][0][3][0] * r_ + bg0; *(f32x4*)(e + 4) = acc[1][0][3][1] * r_ + bg1;
;                 if (fr == 15) { const f32x4 bv0 = *(const f32x4*)(bpg + 128), bv1 = *(const f32x4*)(bpg + 132); float* ev = edge + ((size_t)u.pm * 6 + 5) * DFF + f0; *(f32x4*)ev = acc[1][1][3][0] * r_ + bv0; *(f32x4*)(ev + 4) = acc[1][1][3][1] * r_ + bv1; }
;             }
.LBB0_350:
	s_or_b64 exec, exec, s[6:7]
	s_and_b64 exec, exec, s[44:45]
	s_cbranch_execz .LBB0_352
	v_pk_fma_f32 v[146:147], v[146:147], v[150:151], v[248:249] op_sel_hi:[1,0,1]
	v_pk_fma_f32 v[144:145], v[144:145], v[150:151], v[246:247] op_sel_hi:[1,0,1]
	v_lshl_add_u32 v149, v149, 2, v175
	v_pk_fma_f32 v[142:143], v[150:151], v[142:143], v[244:245] op_sel_hi:[0,1,1]
	v_pk_fma_f32 v[140:141], v[150:151], v[140:141], v[242:243] op_sel_hi:[0,1,1]
	ds_write_b128 v149, v[144:147]
	ds_write_b128 v149, v[140:143] offset:16
.LBB0_352:
	s_or_b64 exec, exec, s[0:1]
	v_mov_b32_e32 v149, v2
	v_lshl_or_b32 v212, s34, 7, v176
	v_lshl_add_u64 v[192:193], s[4:5], 0, v[148:149]
	v_ashrrev_i32_e32 v213, 31, v212
	s_and_saveexec_b64 s[0:1], s[36:37]
	s_cbranch_execz .LBB0_355
	s_mul_i32 s4, s80, 6
	v_or_b32_e32 v142, s4, v174
	v_mov_b64_e32 v[140:141], s[96:97]
	s_movk_i32 s4, 0x2c00
	s_mul_hi_i32 s6, s80, 6
	v_mad_u64_u32 v[140:141], s[4:5], v142, s4, v[140:141]
	v_mad_i32_i24 v141, s6, v221, v141
	v_lshl_add_u64 v[144:145], v[212:213], 2, v[140:141]
	s_waitcnt vmcnt(0)
	v_pk_fma_f32 v[142:143], v[134:135], v[206:207], v[248:249] op_sel_hi:[1,0,1]
	v_pk_fma_f32 v[140:141], v[132:133], v[206:207], v[246:247] op_sel_hi:[1,0,1]
	global_store_dwordx4 v[144:145], v[140:143], off
	s_nop 1
	v_pk_fma_f32 v[142:143], v[94:95], v[206:207], v[244:245] op_sel_hi:[1,0,1]
	v_pk_fma_f32 v[140:141], v[92:93], v[206:207], v[242:243] op_sel_hi:[1,0,1]
	global_store_dwordx4 v[144:145], v[140:143], off offset:16
	s_and_b64 exec, exec, s[38:39]
	s_cbranch_execz .LBB0_355
	global_load_dwordx4 v[140:143], v[192:193], off offset:512
	global_load_dwordx4 v[144:147], v[192:193], off offset:528
	s_mul_i32 s4, s80, 0x10800
	s_mul_hi_i32 s5, s80, 0x10800
	s_add_u32 s4, s96, s4
	s_addc_u32 s5, s97, s5
	v_lshl_add_u64 v[156:157], v[212:213], 2, s[4:5]
	s_mov_b64 s[4:5], 0xb000
	v_mov_b32_e32 v207, v206
	v_mov_b32_e32 v148, v206
	v_mov_b32_e32 v149, v206
	v_lshl_add_u64 v[158:159], v[156:157], 0, s[4:5]
	v_add_co_u32_e32 v156, vcc, 0xb000, v156
	s_waitcnt vmcnt(1)
	v_pk_fma_f32 v[142:143], v[130:131], v[148:149], v[142:143]
	v_addc_co_u32_e32 v157, vcc, 0, v157, vcc
	v_pk_fma_f32 v[140:141], v[128:129], v[206:207], v[140:141]
	s_waitcnt vmcnt(0)
	v_pk_fma_f32 v[146:147], v[98:99], v[148:149], v[146:147]
	v_pk_fma_f32 v[144:145], v[96:97], v[206:207], v[144:145]
	global_store_dwordx4 v[156:157], v[140:143], off
	global_store_dwordx4 v[158:159], v[144:147], off offset:16
.LBB0_355:
	s_or_b64 exec, exec, s[0:1]
	s_and_saveexec_b64 s[0:1], s[50:51]
	s_xor_b64 s[0:1], exec, s[0:1]
	s_andn2_saveexec_b64 s[0:1], s[0:1]
	s_cbranch_execz .LBB0_361
	v_mad_i64_i32 v[140:141], s[4:5], s80, 6, v[178:179]
	v_mov_b64_e32 v[142:143], s[96:97]
	s_movk_i32 s6, 0x2c00
	v_mad_u64_u32 v[142:143], s[4:5], v140, s6, v[142:143]
	v_mad_i32_i24 v143, v141, s6, v143
	v_lshl_add_u64 v[140:141], v[212:213], 2, v[142:143]
	s_waitcnt vmcnt(0)
	v_pk_fma_f32 v[138:139], v[42:43], v[186:187], v[248:249] op_sel_hi:[1,0,1]
	v_pk_fma_f32 v[136:137], v[40:41], v[186:187], v[246:247] op_sel_hi:[1,0,1]
	v_pk_fma_f32 v[122:123], v[6:7], v[186:187], v[244:245] op_sel_hi:[1,0,1]
	v_pk_fma_f32 v[120:121], v[4:5], v[186:187], v[242:243] op_sel_hi:[1,0,1]
	global_store_dwordx4 v[140:141], v[136:139], off
	global_store_dwordx4 v[140:141], v[120:123], off offset:16
	s_and_saveexec_b64 s[4:5], s[40:41]
	s_cbranch_execz .LBB0_360
	global_load_dwordx4 v[120:123], v[192:193], off offset:512
	global_load_dwordx4 v[136:139], v[192:193], off offset:528
	s_mul_i32 s6, s80, 0x10800
	s_mul_hi_i32 s7, s80, 0x10800
	s_add_u32 s6, s96, s6
	s_addc_u32 s7, s97, s7
	v_lshl_add_u64 v[142:143], v[212:213], 2, s[6:7]
	s_mov_b64 s[6:7], 0xdc00
	v_mov_b32_e32 v187, v186
	v_mov_b32_e32 v140, v186
	v_mov_b32_e32 v141, v186
	v_lshl_add_u64 v[144:145], v[142:143], 0, s[6:7]
	v_add_co_u32_e32 v142, vcc, 0xd000, v142
	s_waitcnt vmcnt(1)
	v_pk_fma_f32 v[122:123], v[38:39], v[140:141], v[122:123]
	v_addc_co_u32_e32 v143, vcc, 0, v143, vcc
	v_pk_fma_f32 v[120:121], v[36:37], v[186:187], v[120:121]
	s_waitcnt vmcnt(0)
	v_pk_fma_f32 v[138:139], v[10:11], v[140:141], v[138:139]
	v_pk_fma_f32 v[136:137], v[8:9], v[186:187], v[136:137]
	global_store_dwordx4 v[142:143], v[120:123], off offset:3072
	global_store_dwordx4 v[144:145], v[136:139], off offset:16
